# split-K sample-row epilogue software-pipelined: gate loads of the next row group issued before the current group is processed (two register sets, counted vmcnt)
# speedup vs baseline: 1.0030x; 1.0030x over previous
.LBB0_1162:
	s_ashr_i32 s17, s59, 31
	s_lshr_b32 s17, s17, 30
	s_add_i32 s17, s59, s17
	s_ashr_i32 s26, s17, 2
	s_ashr_i32 s27, s26, 31
	s_lshl_b64 s[26:27], s[26:27], 21
	s_add_u32 s26, s50, s26
	s_addc_u32 s27, s51, s27
	s_lshl_b32 s17, s54, 8
	v_add_u32_e32 v68, s17, v222
	v_ashrrev_i32_e32 v66, 2, v68
	v_or_b32_e32 v69, 8, v66
	v_mov_b64_e32 v[66:67], s[10:11]
	v_lshl_add_u64 v[64:65], s[26:27], 0, v[160:161]
	v_mad_i64_i32 v[70:71], s[26:27], v69, s33, v[66:67]
	v_ashrrev_i32_e32 v69, 31, v68
	v_lshl_add_u64 v[74:75], v[70:71], 0, v[160:161]
	v_lshlrev_b64 v[70:71], 12, v[68:69]
	v_lshl_add_u64 v[84:85], v[64:65], 0, v[70:71]
	global_load_dwordx4 v[70:73], v[74:75], off
	global_load_dwordx4 v[164:167], v[74:75], off offset:64
	global_load_dwordx4 v[168:171], v[74:75], off offset:512
	global_load_dwordx4 v[172:175], v[74:75], off offset:576
	v_add_u32_e32 v182, s17, v223
	v_ashrrev_i32_e32 v180, 2, v182
	v_or_b32_e32 v180, 8, v180
	v_mad_i64_i32 v[184:185], s[26:27], v180, s33, v[66:67]
	v_ashrrev_i32_e32 v183, 31, v182
	v_lshl_add_u64 v[176:177], v[184:185], 0, v[160:161]
	v_lshlrev_b64 v[182:183], 12, v[182:183]
	v_lshl_add_u64 v[178:179], v[64:65], 0, v[182:183]
	global_load_dwordx4 v[182:185], v[176:177], off
	global_load_dwordx4 v[186:189], v[176:177], off offset:64
	global_load_dwordx4 v[190:193], v[176:177], off offset:512
	global_load_dwordx4 v[232:235], v[176:177], off offset:576
	s_waitcnt vmcnt(7)
	v_pk_add_f32 v[72:73], v[72:73], 1.0 op_sel_hi:[1,0]
	v_pk_add_f32 v[70:71], v[70:71], 1.0 op_sel_hi:[1,0]
	v_pk_mul_f32 v[72:73], v[142:143], v[72:73]
	v_pk_mul_f32 v[70:71], v[140:141], v[70:71]
	global_store_dwordx4 v[84:85], v[70:73], off
	s_waitcnt vmcnt(7)
	v_pk_add_f32 v[166:167], v[166:167], 1.0 op_sel_hi:[1,0]
	v_pk_add_f32 v[164:165], v[164:165], 1.0 op_sel_hi:[1,0]
	v_pk_mul_f32 v[166:167], v[138:139], v[166:167]
	v_pk_mul_f32 v[164:165], v[136:137], v[164:165]
	global_store_dwordx4 v[84:85], v[164:167], off offset:64
	s_waitcnt vmcnt(7)
	v_pk_add_f32 v[170:171], v[170:171], 1.0 op_sel_hi:[1,0]
	v_pk_add_f32 v[168:169], v[168:169], 1.0 op_sel_hi:[1,0]
	v_pk_mul_f32 v[170:171], v[134:135], v[170:171]
	v_pk_mul_f32 v[168:169], v[132:133], v[168:169]
	global_store_dwordx4 v[84:85], v[168:171], off offset:512
	s_waitcnt vmcnt(7)
	v_pk_add_f32 v[174:175], v[174:175], 1.0 op_sel_hi:[1,0]
	v_pk_add_f32 v[172:173], v[172:173], 1.0 op_sel_hi:[1,0]
	v_pk_mul_f32 v[174:175], v[130:131], v[174:175]
	v_pk_mul_f32 v[172:173], v[128:129], v[172:173]
	global_store_dwordx4 v[84:85], v[172:175], off offset:576
	s_nop 1
	v_add_u32_e32 v70, s17, v224
	v_ashrrev_i32_e32 v69, 2, v70
	v_add_u32_e32 v69, 8, v69
	v_mad_i64_i32 v[72:73], s[26:27], v69, s33, v[66:67]
	v_ashrrev_i32_e32 v71, 31, v70
	v_lshl_add_u64 v[74:75], v[72:73], 0, v[160:161]
	v_lshlrev_b64 v[70:71], 12, v[70:71]
	v_lshl_add_u64 v[84:85], v[64:65], 0, v[70:71]
	global_load_dwordx4 v[70:73], v[74:75], off
	global_load_dwordx4 v[164:167], v[74:75], off offset:64
	global_load_dwordx4 v[168:171], v[74:75], off offset:512
	global_load_dwordx4 v[172:175], v[74:75], off offset:576
	s_waitcnt vmcnt(11)
	v_pk_add_f32 v[184:185], v[184:185], 1.0 op_sel_hi:[1,0]
	v_pk_add_f32 v[182:183], v[182:183], 1.0 op_sel_hi:[1,0]
	v_pk_mul_f32 v[184:185], v[126:127], v[184:185]
	v_pk_mul_f32 v[182:183], v[124:125], v[182:183]
	global_store_dwordx4 v[178:179], v[182:185], off
	s_waitcnt vmcnt(11)
	v_pk_add_f32 v[188:189], v[188:189], 1.0 op_sel_hi:[1,0]
	v_pk_add_f32 v[186:187], v[186:187], 1.0 op_sel_hi:[1,0]
	v_pk_mul_f32 v[188:189], v[122:123], v[188:189]
	v_pk_mul_f32 v[186:187], v[120:121], v[186:187]
	global_store_dwordx4 v[178:179], v[186:189], off offset:64
	s_waitcnt vmcnt(11)
	v_pk_add_f32 v[192:193], v[192:193], 1.0 op_sel_hi:[1,0]
	v_pk_add_f32 v[190:191], v[190:191], 1.0 op_sel_hi:[1,0]
	v_pk_mul_f32 v[192:193], v[118:119], v[192:193]
	v_pk_mul_f32 v[190:191], v[116:117], v[190:191]
	global_store_dwordx4 v[178:179], v[190:193], off offset:512
	s_waitcnt vmcnt(11)
	v_pk_add_f32 v[234:235], v[234:235], 1.0 op_sel_hi:[1,0]
	v_pk_add_f32 v[232:233], v[232:233], 1.0 op_sel_hi:[1,0]
	v_pk_mul_f32 v[234:235], v[114:115], v[234:235]
	v_pk_mul_f32 v[232:233], v[112:113], v[232:233]
	global_store_dwordx4 v[178:179], v[232:235], off offset:576
	s_nop 1
	v_add_u32_e32 v182, s17, v225
	v_ashrrev_i32_e32 v180, 2, v182
	v_add_u32_e32 v180, 8, v180
	v_mad_i64_i32 v[184:185], s[26:27], v180, s33, v[66:67]
	v_ashrrev_i32_e32 v183, 31, v182
	v_lshl_add_u64 v[176:177], v[184:185], 0, v[160:161]
	v_lshlrev_b64 v[182:183], 12, v[182:183]
	v_lshl_add_u64 v[178:179], v[64:65], 0, v[182:183]
	global_load_dwordx4 v[182:185], v[176:177], off
	global_load_dwordx4 v[186:189], v[176:177], off offset:64
	global_load_dwordx4 v[190:193], v[176:177], off offset:512
	global_load_dwordx4 v[232:235], v[176:177], off offset:576
	s_waitcnt vmcnt(11)
	v_pk_add_f32 v[72:73], v[72:73], 1.0 op_sel_hi:[1,0]
	v_pk_add_f32 v[70:71], v[70:71], 1.0 op_sel_hi:[1,0]
	v_pk_mul_f32 v[72:73], v[110:111], v[72:73]
	v_pk_mul_f32 v[70:71], v[108:109], v[70:71]
	global_store_dwordx4 v[84:85], v[70:73], off
	s_waitcnt vmcnt(11)
	v_pk_add_f32 v[166:167], v[166:167], 1.0 op_sel_hi:[1,0]
	v_pk_add_f32 v[164:165], v[164:165], 1.0 op_sel_hi:[1,0]
	v_pk_mul_f32 v[166:167], v[106:107], v[166:167]
	v_pk_mul_f32 v[164:165], v[104:105], v[164:165]
	global_store_dwordx4 v[84:85], v[164:167], off offset:64
	s_waitcnt vmcnt(11)
	v_pk_add_f32 v[170:171], v[170:171], 1.0 op_sel_hi:[1,0]
	v_pk_add_f32 v[168:169], v[168:169], 1.0 op_sel_hi:[1,0]
	v_pk_mul_f32 v[170:171], v[102:103], v[170:171]
	v_pk_mul_f32 v[168:169], v[100:101], v[168:169]
	global_store_dwordx4 v[84:85], v[168:171], off offset:512
	s_waitcnt vmcnt(11)
	v_pk_add_f32 v[174:175], v[174:175], 1.0 op_sel_hi:[1,0]
	v_pk_add_f32 v[172:173], v[172:173], 1.0 op_sel_hi:[1,0]
	v_pk_mul_f32 v[174:175], v[98:99], v[174:175]
	v_pk_mul_f32 v[172:173], v[96:97], v[172:173]
	global_store_dwordx4 v[84:85], v[172:175], off offset:576
	s_nop 1
	v_add_u32_e32 v70, 0x80, v68
	v_ashrrev_i32_e32 v69, 2, v70
	v_or_b32_e32 v69, 8, v69
	v_mad_i64_i32 v[72:73], s[26:27], v69, s33, v[66:67]
	v_ashrrev_i32_e32 v71, 31, v70
	v_lshl_add_u64 v[74:75], v[72:73], 0, v[160:161]
	v_lshlrev_b64 v[70:71], 12, v[70:71]
	v_lshl_add_u64 v[84:85], v[64:65], 0, v[70:71]
	global_load_dwordx4 v[70:73], v[74:75], off
	global_load_dwordx4 v[164:167], v[74:75], off offset:64
	global_load_dwordx4 v[168:171], v[74:75], off offset:512
	global_load_dwordx4 v[172:175], v[74:75], off offset:576
	s_waitcnt vmcnt(11)
	v_pk_add_f32 v[184:185], v[184:185], 1.0 op_sel_hi:[1,0]
	v_pk_add_f32 v[182:183], v[182:183], 1.0 op_sel_hi:[1,0]
	v_pk_mul_f32 v[184:185], v[94:95], v[184:185]
	v_pk_mul_f32 v[182:183], v[92:93], v[182:183]
	global_store_dwordx4 v[178:179], v[182:185], off
	s_waitcnt vmcnt(11)
	v_pk_add_f32 v[188:189], v[188:189], 1.0 op_sel_hi:[1,0]
	v_pk_add_f32 v[186:187], v[186:187], 1.0 op_sel_hi:[1,0]
	v_pk_mul_f32 v[188:189], v[90:91], v[188:189]
	v_pk_mul_f32 v[186:187], v[88:89], v[186:187]
	global_store_dwordx4 v[178:179], v[186:189], off offset:64
	s_waitcnt vmcnt(11)
	v_pk_add_f32 v[192:193], v[192:193], 1.0 op_sel_hi:[1,0]
	v_pk_add_f32 v[190:191], v[190:191], 1.0 op_sel_hi:[1,0]
	v_pk_mul_f32 v[192:193], v[82:83], v[192:193]
	v_pk_mul_f32 v[190:191], v[80:81], v[190:191]
	global_store_dwordx4 v[178:179], v[190:193], off offset:512
	s_waitcnt vmcnt(11)
	v_pk_add_f32 v[234:235], v[234:235], 1.0 op_sel_hi:[1,0]
	v_pk_add_f32 v[232:233], v[232:233], 1.0 op_sel_hi:[1,0]
	v_pk_mul_f32 v[234:235], v[78:79], v[234:235]
	v_pk_mul_f32 v[232:233], v[76:77], v[232:233]
	global_store_dwordx4 v[178:179], v[232:235], off offset:576
	s_nop 1
	v_add_u32_e32 v182, 0x90, v68
	v_ashrrev_i32_e32 v180, 2, v182
	v_or_b32_e32 v180, 8, v180
	v_mad_i64_i32 v[184:185], s[26:27], v180, s33, v[66:67]
	v_ashrrev_i32_e32 v183, 31, v182
	v_lshl_add_u64 v[176:177], v[184:185], 0, v[160:161]
	v_lshlrev_b64 v[182:183], 12, v[182:183]
	v_lshl_add_u64 v[178:179], v[64:65], 0, v[182:183]
	global_load_dwordx4 v[182:185], v[176:177], off
	global_load_dwordx4 v[186:189], v[176:177], off offset:64
	global_load_dwordx4 v[190:193], v[176:177], off offset:512
	global_load_dwordx4 v[232:235], v[176:177], off offset:576
	s_waitcnt vmcnt(11)
	v_pk_add_f32 v[72:73], v[72:73], 1.0 op_sel_hi:[1,0]
	v_pk_add_f32 v[70:71], v[70:71], 1.0 op_sel_hi:[1,0]
	v_pk_mul_f32 v[72:73], v[62:63], v[72:73]
	v_pk_mul_f32 v[70:71], v[60:61], v[70:71]
	global_store_dwordx4 v[84:85], v[70:73], off
	s_waitcnt vmcnt(11)
	v_pk_add_f32 v[166:167], v[166:167], 1.0 op_sel_hi:[1,0]
	v_pk_add_f32 v[164:165], v[164:165], 1.0 op_sel_hi:[1,0]
	v_pk_mul_f32 v[166:167], v[58:59], v[166:167]
	v_pk_mul_f32 v[164:165], v[56:57], v[164:165]
	global_store_dwordx4 v[84:85], v[164:167], off offset:64
	s_waitcnt vmcnt(11)
	v_pk_add_f32 v[170:171], v[170:171], 1.0 op_sel_hi:[1,0]
	v_pk_add_f32 v[168:169], v[168:169], 1.0 op_sel_hi:[1,0]
	v_pk_mul_f32 v[170:171], v[54:55], v[170:171]
	v_pk_mul_f32 v[168:169], v[52:53], v[168:169]
	global_store_dwordx4 v[84:85], v[168:171], off offset:512
	s_waitcnt vmcnt(11)
	v_pk_add_f32 v[174:175], v[174:175], 1.0 op_sel_hi:[1,0]
	v_pk_add_f32 v[172:173], v[172:173], 1.0 op_sel_hi:[1,0]
	v_pk_mul_f32 v[174:175], v[50:51], v[174:175]
	v_pk_mul_f32 v[172:173], v[48:49], v[172:173]
	global_store_dwordx4 v[84:85], v[172:175], off offset:576
	s_nop 1
	v_add_u32_e32 v70, 0xa0, v68
	v_ashrrev_i32_e32 v69, 2, v70
	v_add_u32_e32 v69, 8, v69
	v_mad_i64_i32 v[72:73], s[26:27], v69, s33, v[66:67]
	v_ashrrev_i32_e32 v71, 31, v70
	v_lshl_add_u64 v[74:75], v[72:73], 0, v[160:161]
	v_lshlrev_b64 v[70:71], 12, v[70:71]
	v_lshl_add_u64 v[84:85], v[64:65], 0, v[70:71]
	global_load_dwordx4 v[70:73], v[74:75], off
	global_load_dwordx4 v[164:167], v[74:75], off offset:64
	global_load_dwordx4 v[168:171], v[74:75], off offset:512
	global_load_dwordx4 v[172:175], v[74:75], off offset:576
	s_waitcnt vmcnt(11)
	v_pk_add_f32 v[184:185], v[184:185], 1.0 op_sel_hi:[1,0]
	v_pk_add_f32 v[182:183], v[182:183], 1.0 op_sel_hi:[1,0]
	v_pk_mul_f32 v[184:185], v[46:47], v[184:185]
	v_pk_mul_f32 v[182:183], v[44:45], v[182:183]
	global_store_dwordx4 v[178:179], v[182:185], off
	s_waitcnt vmcnt(11)
	v_pk_add_f32 v[188:189], v[188:189], 1.0 op_sel_hi:[1,0]
	v_pk_add_f32 v[186:187], v[186:187], 1.0 op_sel_hi:[1,0]
	v_pk_mul_f32 v[188:189], v[42:43], v[188:189]
	v_pk_mul_f32 v[186:187], v[40:41], v[186:187]
	global_store_dwordx4 v[178:179], v[186:189], off offset:64
	s_waitcnt vmcnt(11)
	v_pk_add_f32 v[192:193], v[192:193], 1.0 op_sel_hi:[1,0]
	v_pk_add_f32 v[190:191], v[190:191], 1.0 op_sel_hi:[1,0]
	v_pk_mul_f32 v[192:193], v[38:39], v[192:193]
	v_pk_mul_f32 v[190:191], v[36:37], v[190:191]
	global_store_dwordx4 v[178:179], v[190:193], off offset:512
	s_waitcnt vmcnt(11)
	v_pk_add_f32 v[234:235], v[234:235], 1.0 op_sel_hi:[1,0]
	v_pk_add_f32 v[232:233], v[232:233], 1.0 op_sel_hi:[1,0]
	v_pk_mul_f32 v[234:235], v[34:35], v[234:235]
	v_pk_mul_f32 v[232:233], v[32:33], v[232:233]
	global_store_dwordx4 v[178:179], v[232:235], off offset:576
	s_nop 1
	v_add_u32_e32 v68, 0xb0, v68
	v_ashrrev_i32_e32 v69, 2, v68
	v_add_u32_e32 v69, 8, v69
	v_mad_i64_i32 v[66:67], s[26:27], v69, s33, v[66:67]
	v_ashrrev_i32_e32 v69, 31, v68
	s_waitcnt vmcnt(7)
	v_pk_add_f32 v[72:73], v[72:73], 1.0 op_sel_hi:[1,0]
	v_pk_add_f32 v[70:71], v[70:71], 1.0 op_sel_hi:[1,0]
	v_pk_mul_f32 v[72:73], v[30:31], v[72:73]
	v_pk_mul_f32 v[70:71], v[28:29], v[70:71]
	global_store_dwordx4 v[84:85], v[70:73], off
	s_waitcnt vmcnt(7)
	v_pk_add_f32 v[166:167], v[166:167], 1.0 op_sel_hi:[1,0]
	v_pk_add_f32 v[164:165], v[164:165], 1.0 op_sel_hi:[1,0]
	v_pk_mul_f32 v[166:167], v[26:27], v[166:167]
	v_pk_mul_f32 v[164:165], v[24:25], v[164:165]
	global_store_dwordx4 v[84:85], v[164:167], off offset:64
	s_waitcnt vmcnt(7)
	v_pk_add_f32 v[170:171], v[170:171], 1.0 op_sel_hi:[1,0]
	v_pk_add_f32 v[168:169], v[168:169], 1.0 op_sel_hi:[1,0]
	v_pk_mul_f32 v[170:171], v[22:23], v[170:171]
	v_pk_mul_f32 v[168:169], v[20:21], v[168:169]
	global_store_dwordx4 v[84:85], v[168:171], off offset:512
	s_waitcnt vmcnt(7)
	v_pk_add_f32 v[174:175], v[174:175], 1.0 op_sel_hi:[1,0]
	v_pk_add_f32 v[172:173], v[172:173], 1.0 op_sel_hi:[1,0]
	v_pk_mul_f32 v[174:175], v[18:19], v[174:175]
	v_pk_mul_f32 v[172:173], v[16:17], v[172:173]
	global_store_dwordx4 v[84:85], v[172:175], off offset:576
	s_nop 1
	v_lshl_add_u64 v[70:71], v[66:67], 0, v[160:161]
	v_lshlrev_b64 v[66:67], 12, v[68:69]
	v_lshl_add_u64 v[68:69], v[64:65], 0, v[66:67]
	global_load_dwordx4 v[64:67], v[70:71], off
	global_load_dwordx4 v[164:167], v[70:71], off offset:64
	global_load_dwordx4 v[168:171], v[70:71], off offset:512
	global_load_dwordx4 v[172:175], v[70:71], off offset:576
	s_waitcnt vmcnt(3)
	v_pk_add_f32 v[66:67], v[66:67], 1.0 op_sel_hi:[1,0]
	v_pk_add_f32 v[64:65], v[64:65], 1.0 op_sel_hi:[1,0]
	v_pk_mul_f32 v[66:67], v[14:15], v[66:67]
	v_pk_mul_f32 v[64:65], v[12:13], v[64:65]
	global_store_dwordx4 v[68:69], v[64:67], off
	s_waitcnt vmcnt(3)
	v_pk_add_f32 v[166:167], v[166:167], 1.0 op_sel_hi:[1,0]
	v_pk_add_f32 v[164:165], v[164:165], 1.0 op_sel_hi:[1,0]
	v_pk_mul_f32 v[166:167], v[10:11], v[166:167]
	v_pk_mul_f32 v[164:165], v[8:9], v[164:165]
	global_store_dwordx4 v[68:69], v[164:167], off offset:64
	s_waitcnt vmcnt(3)
	v_pk_add_f32 v[170:171], v[170:171], 1.0 op_sel_hi:[1,0]
	v_pk_add_f32 v[168:169], v[168:169], 1.0 op_sel_hi:[1,0]
	v_pk_mul_f32 v[170:171], v[6:7], v[170:171]
	v_pk_mul_f32 v[168:169], v[4:5], v[168:169]
	global_store_dwordx4 v[68:69], v[168:171], off offset:512
	s_waitcnt vmcnt(3)
	v_pk_add_f32 v[174:175], v[174:175], 1.0 op_sel_hi:[1,0]
	v_pk_add_f32 v[172:173], v[172:173], 1.0 op_sel_hi:[1,0]
	v_pk_mul_f32 v[174:175], v[2:3], v[174:175]
	v_pk_mul_f32 v[172:173], v[0:1], v[172:173]
	global_store_dwordx4 v[68:69], v[172:175], off offset:576
	s_cbranch_execnz .LBB0_1161

.LBB0_1377:
	s_ashr_i32 s25, s77, 31
	s_lshr_b32 s25, s25, 30
	s_add_i32 s25, s77, s25
	s_ashr_i32 s34, s25, 2
	s_ashr_i32 s35, s34, 31
	s_lshl_b64 s[34:35], s[34:35], 21
	s_add_u32 s34, s59, s34
	s_addc_u32 s35, s70, s35
	s_lshl_b32 s25, s76, 8
	v_add_u32_e32 v132, s25, v222
	v_ashrrev_i32_e32 v130, 2, v132
	v_or_b32_e32 v133, 8, v130
	v_mov_b64_e32 v[130:131], s[12:13]
	v_lshl_add_u64 v[128:129], s[34:35], 0, v[160:161]
	v_mad_i64_i32 v[134:135], s[34:35], v133, s33, v[130:131]
	v_ashrrev_i32_e32 v133, 31, v132
	v_lshl_add_u64 v[138:139], v[134:135], 0, v[160:161]
	v_lshlrev_b64 v[134:135], 12, v[132:133]
	v_lshl_add_u64 v[140:141], v[128:129], 0, v[134:135]
	global_load_dwordx4 v[134:137], v[138:139], off
	global_load_dwordx4 v[164:167], v[138:139], off offset:64
	global_load_dwordx4 v[168:171], v[138:139], off offset:512
	global_load_dwordx4 v[172:175], v[138:139], off offset:576
	v_add_u32_e32 v182, s25, v223
	v_ashrrev_i32_e32 v180, 2, v182
	v_or_b32_e32 v180, 8, v180
	v_mad_i64_i32 v[184:185], s[34:35], v180, s33, v[130:131]
	v_ashrrev_i32_e32 v183, 31, v182
	v_lshl_add_u64 v[176:177], v[184:185], 0, v[160:161]
	v_lshlrev_b64 v[182:183], 12, v[182:183]
	v_lshl_add_u64 v[178:179], v[128:129], 0, v[182:183]
	global_load_dwordx4 v[182:185], v[176:177], off
	global_load_dwordx4 v[186:189], v[176:177], off offset:64
	global_load_dwordx4 v[190:193], v[176:177], off offset:512
	global_load_dwordx4 v[232:235], v[176:177], off offset:576
	s_waitcnt vmcnt(7)
	v_pk_fma_f32 v[136:137], v[136:137], 0.5, 0.5 op_sel_hi:[1,0,0]
	v_pk_fma_f32 v[134:135], v[134:135], 0.5, 0.5 op_sel_hi:[1,0,0]
	v_pk_mul_f32 v[136:137], v[126:127], v[136:137]
	v_pk_mul_f32 v[134:135], v[124:125], v[134:135]
	global_store_dwordx4 v[140:141], v[134:137], off
	s_waitcnt vmcnt(7)
	v_pk_fma_f32 v[166:167], v[166:167], 0.5, 0.5 op_sel_hi:[1,0,0]
	v_pk_fma_f32 v[164:165], v[164:165], 0.5, 0.5 op_sel_hi:[1,0,0]
	v_pk_mul_f32 v[166:167], v[122:123], v[166:167]
	v_pk_mul_f32 v[164:165], v[120:121], v[164:165]
	global_store_dwordx4 v[140:141], v[164:167], off offset:64
	s_waitcnt vmcnt(7)
	v_pk_fma_f32 v[170:171], v[170:171], 0.5, 0.5 op_sel_hi:[1,0,0]
	v_pk_fma_f32 v[168:169], v[168:169], 0.5, 0.5 op_sel_hi:[1,0,0]
	v_pk_mul_f32 v[170:171], v[118:119], v[170:171]
	v_pk_mul_f32 v[168:169], v[116:117], v[168:169]
	global_store_dwordx4 v[140:141], v[168:171], off offset:512
	s_waitcnt vmcnt(7)
	v_pk_fma_f32 v[174:175], v[174:175], 0.5, 0.5 op_sel_hi:[1,0,0]
	v_pk_fma_f32 v[172:173], v[172:173], 0.5, 0.5 op_sel_hi:[1,0,0]
	v_pk_mul_f32 v[174:175], v[114:115], v[174:175]
	v_pk_mul_f32 v[172:173], v[112:113], v[172:173]
	global_store_dwordx4 v[140:141], v[172:175], off offset:576
	s_nop 1
	v_add_u32_e32 v134, s25, v224
	v_ashrrev_i32_e32 v133, 2, v134
	v_add_u32_e32 v133, 8, v133
	v_mad_i64_i32 v[136:137], s[34:35], v133, s33, v[130:131]
	v_ashrrev_i32_e32 v135, 31, v134
	v_lshl_add_u64 v[138:139], v[136:137], 0, v[160:161]
	v_lshlrev_b64 v[134:135], 12, v[134:135]
	v_lshl_add_u64 v[140:141], v[128:129], 0, v[134:135]
	global_load_dwordx4 v[134:137], v[138:139], off
	global_load_dwordx4 v[164:167], v[138:139], off offset:64
	global_load_dwordx4 v[168:171], v[138:139], off offset:512
	global_load_dwordx4 v[172:175], v[138:139], off offset:576
	s_waitcnt vmcnt(11)
	v_pk_fma_f32 v[184:185], v[184:185], 0.5, 0.5 op_sel_hi:[1,0,0]
	v_pk_fma_f32 v[182:183], v[182:183], 0.5, 0.5 op_sel_hi:[1,0,0]
	v_pk_mul_f32 v[184:185], v[110:111], v[184:185]
	v_pk_mul_f32 v[182:183], v[108:109], v[182:183]
	global_store_dwordx4 v[178:179], v[182:185], off
	s_waitcnt vmcnt(11)
	v_pk_fma_f32 v[188:189], v[188:189], 0.5, 0.5 op_sel_hi:[1,0,0]
	v_pk_fma_f32 v[186:187], v[186:187], 0.5, 0.5 op_sel_hi:[1,0,0]
	v_pk_mul_f32 v[188:189], v[106:107], v[188:189]
	v_pk_mul_f32 v[186:187], v[104:105], v[186:187]
	global_store_dwordx4 v[178:179], v[186:189], off offset:64
	s_waitcnt vmcnt(11)
	v_pk_fma_f32 v[192:193], v[192:193], 0.5, 0.5 op_sel_hi:[1,0,0]
	v_pk_fma_f32 v[190:191], v[190:191], 0.5, 0.5 op_sel_hi:[1,0,0]
	v_pk_mul_f32 v[192:193], v[102:103], v[192:193]
	v_pk_mul_f32 v[190:191], v[100:101], v[190:191]
	global_store_dwordx4 v[178:179], v[190:193], off offset:512
	s_waitcnt vmcnt(11)
	v_pk_fma_f32 v[234:235], v[234:235], 0.5, 0.5 op_sel_hi:[1,0,0]
	v_pk_fma_f32 v[232:233], v[232:233], 0.5, 0.5 op_sel_hi:[1,0,0]
	v_pk_mul_f32 v[234:235], v[98:99], v[234:235]
	v_pk_mul_f32 v[232:233], v[96:97], v[232:233]
	global_store_dwordx4 v[178:179], v[232:235], off offset:576
	s_nop 1
	v_add_u32_e32 v182, s25, v225
	v_ashrrev_i32_e32 v180, 2, v182
	v_add_u32_e32 v180, 8, v180
	v_mad_i64_i32 v[184:185], s[34:35], v180, s33, v[130:131]
	v_ashrrev_i32_e32 v183, 31, v182
	v_lshl_add_u64 v[176:177], v[184:185], 0, v[160:161]
	v_lshlrev_b64 v[182:183], 12, v[182:183]
	v_lshl_add_u64 v[178:179], v[128:129], 0, v[182:183]
	global_load_dwordx4 v[182:185], v[176:177], off
	global_load_dwordx4 v[186:189], v[176:177], off offset:64
	global_load_dwordx4 v[190:193], v[176:177], off offset:512
	global_load_dwordx4 v[232:235], v[176:177], off offset:576
	s_waitcnt vmcnt(11)
	v_pk_fma_f32 v[136:137], v[136:137], 0.5, 0.5 op_sel_hi:[1,0,0]
	v_pk_fma_f32 v[134:135], v[134:135], 0.5, 0.5 op_sel_hi:[1,0,0]
	v_pk_mul_f32 v[136:137], v[94:95], v[136:137]
	v_pk_mul_f32 v[134:135], v[92:93], v[134:135]
	global_store_dwordx4 v[140:141], v[134:137], off
	s_waitcnt vmcnt(11)
	v_pk_fma_f32 v[166:167], v[166:167], 0.5, 0.5 op_sel_hi:[1,0,0]
	v_pk_fma_f32 v[164:165], v[164:165], 0.5, 0.5 op_sel_hi:[1,0,0]
	v_pk_mul_f32 v[166:167], v[90:91], v[166:167]
	v_pk_mul_f32 v[164:165], v[88:89], v[164:165]
	global_store_dwordx4 v[140:141], v[164:167], off offset:64
	s_waitcnt vmcnt(11)
	v_pk_fma_f32 v[170:171], v[170:171], 0.5, 0.5 op_sel_hi:[1,0,0]
	v_pk_fma_f32 v[168:169], v[168:169], 0.5, 0.5 op_sel_hi:[1,0,0]
	v_pk_mul_f32 v[170:171], v[86:87], v[170:171]
	v_pk_mul_f32 v[168:169], v[84:85], v[168:169]
	global_store_dwordx4 v[140:141], v[168:171], off offset:512
	s_waitcnt vmcnt(11)
	v_pk_fma_f32 v[174:175], v[174:175], 0.5, 0.5 op_sel_hi:[1,0,0]
	v_pk_fma_f32 v[172:173], v[172:173], 0.5, 0.5 op_sel_hi:[1,0,0]
	v_pk_mul_f32 v[174:175], v[82:83], v[174:175]
	v_pk_mul_f32 v[172:173], v[80:81], v[172:173]
	global_store_dwordx4 v[140:141], v[172:175], off offset:576
	s_nop 1
	v_add_u32_e32 v134, 0x80, v132
	v_ashrrev_i32_e32 v133, 2, v134
	v_or_b32_e32 v133, 8, v133
	v_mad_i64_i32 v[136:137], s[34:35], v133, s33, v[130:131]
	v_ashrrev_i32_e32 v135, 31, v134
	v_lshl_add_u64 v[138:139], v[136:137], 0, v[160:161]
	v_lshlrev_b64 v[134:135], 12, v[134:135]
	v_lshl_add_u64 v[140:141], v[128:129], 0, v[134:135]
	global_load_dwordx4 v[134:137], v[138:139], off
	global_load_dwordx4 v[164:167], v[138:139], off offset:64
	global_load_dwordx4 v[168:171], v[138:139], off offset:512
	global_load_dwordx4 v[172:175], v[138:139], off offset:576
	s_waitcnt vmcnt(11)
	v_pk_fma_f32 v[184:185], v[184:185], 0.5, 0.5 op_sel_hi:[1,0,0]
	v_pk_fma_f32 v[182:183], v[182:183], 0.5, 0.5 op_sel_hi:[1,0,0]
	v_pk_mul_f32 v[184:185], v[78:79], v[184:185]
	v_pk_mul_f32 v[182:183], v[76:77], v[182:183]
	global_store_dwordx4 v[178:179], v[182:185], off
	s_waitcnt vmcnt(11)
	v_pk_fma_f32 v[188:189], v[188:189], 0.5, 0.5 op_sel_hi:[1,0,0]
	v_pk_fma_f32 v[186:187], v[186:187], 0.5, 0.5 op_sel_hi:[1,0,0]
	v_pk_mul_f32 v[188:189], v[74:75], v[188:189]
	v_pk_mul_f32 v[186:187], v[72:73], v[186:187]
	global_store_dwordx4 v[178:179], v[186:189], off offset:64
	s_waitcnt vmcnt(11)
	v_pk_fma_f32 v[192:193], v[192:193], 0.5, 0.5 op_sel_hi:[1,0,0]
	v_pk_fma_f32 v[190:191], v[190:191], 0.5, 0.5 op_sel_hi:[1,0,0]
	v_pk_mul_f32 v[192:193], v[70:71], v[192:193]
	v_pk_mul_f32 v[190:191], v[68:69], v[190:191]
	global_store_dwordx4 v[178:179], v[190:193], off offset:512
	s_waitcnt vmcnt(11)
	v_pk_fma_f32 v[234:235], v[234:235], 0.5, 0.5 op_sel_hi:[1,0,0]
	v_pk_fma_f32 v[232:233], v[232:233], 0.5, 0.5 op_sel_hi:[1,0,0]
	v_pk_mul_f32 v[234:235], v[66:67], v[234:235]
	v_pk_mul_f32 v[232:233], v[64:65], v[232:233]
	global_store_dwordx4 v[178:179], v[232:235], off offset:576
	s_nop 1
	v_add_u32_e32 v182, 0x90, v132
	v_ashrrev_i32_e32 v180, 2, v182
	v_or_b32_e32 v180, 8, v180
	v_mad_i64_i32 v[184:185], s[34:35], v180, s33, v[130:131]
	v_ashrrev_i32_e32 v183, 31, v182
	v_lshl_add_u64 v[176:177], v[184:185], 0, v[160:161]
	v_lshlrev_b64 v[182:183], 12, v[182:183]
	v_lshl_add_u64 v[178:179], v[128:129], 0, v[182:183]
	global_load_dwordx4 v[182:185], v[176:177], off
	global_load_dwordx4 v[186:189], v[176:177], off offset:64
	global_load_dwordx4 v[190:193], v[176:177], off offset:512
	global_load_dwordx4 v[232:235], v[176:177], off offset:576
	s_waitcnt vmcnt(11)
	v_pk_fma_f32 v[136:137], v[136:137], 0.5, 0.5 op_sel_hi:[1,0,0]
	v_pk_fma_f32 v[134:135], v[134:135], 0.5, 0.5 op_sel_hi:[1,0,0]
	v_pk_mul_f32 v[136:137], v[62:63], v[136:137]
	v_pk_mul_f32 v[134:135], v[60:61], v[134:135]
	global_store_dwordx4 v[140:141], v[134:137], off
	s_waitcnt vmcnt(11)
	v_pk_fma_f32 v[166:167], v[166:167], 0.5, 0.5 op_sel_hi:[1,0,0]
	v_pk_fma_f32 v[164:165], v[164:165], 0.5, 0.5 op_sel_hi:[1,0,0]
	v_pk_mul_f32 v[166:167], v[58:59], v[166:167]
	v_pk_mul_f32 v[164:165], v[56:57], v[164:165]
	global_store_dwordx4 v[140:141], v[164:167], off offset:64
	s_waitcnt vmcnt(11)
	v_pk_fma_f32 v[170:171], v[170:171], 0.5, 0.5 op_sel_hi:[1,0,0]
	v_pk_fma_f32 v[168:169], v[168:169], 0.5, 0.5 op_sel_hi:[1,0,0]
	v_pk_mul_f32 v[170:171], v[54:55], v[170:171]
	v_pk_mul_f32 v[168:169], v[52:53], v[168:169]
	global_store_dwordx4 v[140:141], v[168:171], off offset:512
	s_waitcnt vmcnt(11)
	v_pk_fma_f32 v[174:175], v[174:175], 0.5, 0.5 op_sel_hi:[1,0,0]
	v_pk_fma_f32 v[172:173], v[172:173], 0.5, 0.5 op_sel_hi:[1,0,0]
	v_pk_mul_f32 v[174:175], v[50:51], v[174:175]
	v_pk_mul_f32 v[172:173], v[48:49], v[172:173]
	global_store_dwordx4 v[140:141], v[172:175], off offset:576
	s_nop 1
	v_add_u32_e32 v134, 0xa0, v132
	v_ashrrev_i32_e32 v133, 2, v134
	v_add_u32_e32 v133, 8, v133
	v_mad_i64_i32 v[136:137], s[34:35], v133, s33, v[130:131]
	v_ashrrev_i32_e32 v135, 31, v134
	v_lshl_add_u64 v[138:139], v[136:137], 0, v[160:161]
	v_lshlrev_b64 v[134:135], 12, v[134:135]
	v_lshl_add_u64 v[140:141], v[128:129], 0, v[134:135]
	global_load_dwordx4 v[134:137], v[138:139], off
	global_load_dwordx4 v[164:167], v[138:139], off offset:64
	global_load_dwordx4 v[168:171], v[138:139], off offset:512
	global_load_dwordx4 v[172:175], v[138:139], off offset:576
	s_waitcnt vmcnt(11)
	v_pk_fma_f32 v[184:185], v[184:185], 0.5, 0.5 op_sel_hi:[1,0,0]
	v_pk_fma_f32 v[182:183], v[182:183], 0.5, 0.5 op_sel_hi:[1,0,0]
	v_pk_mul_f32 v[184:185], v[46:47], v[184:185]
	v_pk_mul_f32 v[182:183], v[44:45], v[182:183]
	global_store_dwordx4 v[178:179], v[182:185], off
	s_waitcnt vmcnt(11)
	v_pk_fma_f32 v[188:189], v[188:189], 0.5, 0.5 op_sel_hi:[1,0,0]
	v_pk_fma_f32 v[186:187], v[186:187], 0.5, 0.5 op_sel_hi:[1,0,0]
	v_pk_mul_f32 v[188:189], v[42:43], v[188:189]
	v_pk_mul_f32 v[186:187], v[40:41], v[186:187]
	global_store_dwordx4 v[178:179], v[186:189], off offset:64
	s_waitcnt vmcnt(11)
	v_pk_fma_f32 v[192:193], v[192:193], 0.5, 0.5 op_sel_hi:[1,0,0]
	v_pk_fma_f32 v[190:191], v[190:191], 0.5, 0.5 op_sel_hi:[1,0,0]
	v_pk_mul_f32 v[192:193], v[38:39], v[192:193]
	v_pk_mul_f32 v[190:191], v[36:37], v[190:191]
	global_store_dwordx4 v[178:179], v[190:193], off offset:512
	s_waitcnt vmcnt(11)
	v_pk_fma_f32 v[234:235], v[234:235], 0.5, 0.5 op_sel_hi:[1,0,0]
	v_pk_fma_f32 v[232:233], v[232:233], 0.5, 0.5 op_sel_hi:[1,0,0]
	v_pk_mul_f32 v[234:235], v[34:35], v[234:235]
	v_pk_mul_f32 v[232:233], v[32:33], v[232:233]
	global_store_dwordx4 v[178:179], v[232:235], off offset:576
	s_nop 1
	v_add_u32_e32 v132, 0xb0, v132
	v_ashrrev_i32_e32 v133, 2, v132
	v_add_u32_e32 v133, 8, v133
	v_mad_i64_i32 v[130:131], s[34:35], v133, s33, v[130:131]
	v_ashrrev_i32_e32 v133, 31, v132
	s_waitcnt vmcnt(7)
	v_pk_fma_f32 v[136:137], v[136:137], 0.5, 0.5 op_sel_hi:[1,0,0]
	v_pk_fma_f32 v[134:135], v[134:135], 0.5, 0.5 op_sel_hi:[1,0,0]
	v_pk_mul_f32 v[136:137], v[30:31], v[136:137]
	v_pk_mul_f32 v[134:135], v[28:29], v[134:135]
	global_store_dwordx4 v[140:141], v[134:137], off
	s_waitcnt vmcnt(7)
	v_pk_fma_f32 v[166:167], v[166:167], 0.5, 0.5 op_sel_hi:[1,0,0]
	v_pk_fma_f32 v[164:165], v[164:165], 0.5, 0.5 op_sel_hi:[1,0,0]
	v_pk_mul_f32 v[166:167], v[26:27], v[166:167]
	v_pk_mul_f32 v[164:165], v[24:25], v[164:165]
	global_store_dwordx4 v[140:141], v[164:167], off offset:64
	s_waitcnt vmcnt(7)
	v_pk_fma_f32 v[170:171], v[170:171], 0.5, 0.5 op_sel_hi:[1,0,0]
	v_pk_fma_f32 v[168:169], v[168:169], 0.5, 0.5 op_sel_hi:[1,0,0]
	v_pk_mul_f32 v[170:171], v[22:23], v[170:171]
	v_pk_mul_f32 v[168:169], v[20:21], v[168:169]
	global_store_dwordx4 v[140:141], v[168:171], off offset:512
	s_waitcnt vmcnt(7)
	v_pk_fma_f32 v[174:175], v[174:175], 0.5, 0.5 op_sel_hi:[1,0,0]
	v_pk_fma_f32 v[172:173], v[172:173], 0.5, 0.5 op_sel_hi:[1,0,0]
	v_pk_mul_f32 v[174:175], v[18:19], v[174:175]
	v_pk_mul_f32 v[172:173], v[16:17], v[172:173]
	global_store_dwordx4 v[140:141], v[172:175], off offset:576
	s_nop 1
	v_lshl_add_u64 v[134:135], v[130:131], 0, v[160:161]
	v_lshlrev_b64 v[130:131], 12, v[132:133]
	v_lshl_add_u64 v[132:133], v[128:129], 0, v[130:131]
	global_load_dwordx4 v[128:131], v[134:135], off
	global_load_dwordx4 v[164:167], v[134:135], off offset:64
	global_load_dwordx4 v[168:171], v[134:135], off offset:512
	global_load_dwordx4 v[172:175], v[134:135], off offset:576
	s_waitcnt vmcnt(3)
	v_pk_fma_f32 v[130:131], v[130:131], 0.5, 0.5 op_sel_hi:[1,0,0]
	v_pk_fma_f32 v[128:129], v[128:129], 0.5, 0.5 op_sel_hi:[1,0,0]
	v_pk_mul_f32 v[130:131], v[14:15], v[130:131]
	v_pk_mul_f32 v[128:129], v[12:13], v[128:129]
	global_store_dwordx4 v[132:133], v[128:131], off
	s_waitcnt vmcnt(3)
	v_pk_fma_f32 v[166:167], v[166:167], 0.5, 0.5 op_sel_hi:[1,0,0]
	v_pk_fma_f32 v[164:165], v[164:165], 0.5, 0.5 op_sel_hi:[1,0,0]
	v_pk_mul_f32 v[166:167], v[10:11], v[166:167]
	v_pk_mul_f32 v[164:165], v[8:9], v[164:165]
	global_store_dwordx4 v[132:133], v[164:167], off offset:64
	s_waitcnt vmcnt(3)
	v_pk_fma_f32 v[170:171], v[170:171], 0.5, 0.5 op_sel_hi:[1,0,0]
	v_pk_fma_f32 v[168:169], v[168:169], 0.5, 0.5 op_sel_hi:[1,0,0]
	v_pk_mul_f32 v[170:171], v[6:7], v[170:171]
	v_pk_mul_f32 v[168:169], v[4:5], v[168:169]
	global_store_dwordx4 v[132:133], v[168:171], off offset:512
	s_waitcnt vmcnt(3)
	v_pk_fma_f32 v[174:175], v[174:175], 0.5, 0.5 op_sel_hi:[1,0,0]
	v_pk_fma_f32 v[172:173], v[172:173], 0.5, 0.5 op_sel_hi:[1,0,0]
	v_pk_mul_f32 v[174:175], v[2:3], v[174:175]
	v_pk_mul_f32 v[172:173], v[0:1], v[172:173]
	global_store_dwordx4 v[132:133], v[172:175], off offset:576
	s_cbranch_execnz .LBB0_1376
